# cache_convert: the once-read f32 cache pages are loaded non-temporal (nt)
# baseline (speedup 1.0000x reference)
; __device__ __forceinline__ void cache_convert(const Params& P, const Ctx& C) {
;     ...
;       for (int it = gwv; it < 2 * NSEQ * 16 * 4; it += NGWV) {
;         const int qt = it & 3, sp = (it >> 2) & 2047, ci = it >> 13, seq = sp >> 4, pi = sp & 15;
;         const int page = ((const int*)P.in[8])[seq * 16 + pi];
;         const float* src = P.in[2 + ci] + (size_t)page * (128 * 256) + (size_t)qt * (32 * 256);
;         bf16_t* dst = (bf16_t*)(ws + (ci ? WS_AV : WS_AK)) + 4194304;
;         f32x4 a[16], c[16];
; #pragma unroll
;         for (int j = 0; j < 16; ++j) { const float* sj = src + (size_t)(64 * j) * 8; a[j] = *(const f32x4*)(sj + 8u * lane); c[j] = *(const f32x4*)(sj + 8u * lane + 4); }
.LBB0_281:
	s_bfe_u32 s9, s0, 0x70006
	s_bfe_u32 s8, s0, 0x40002
	s_lshl_b32 s10, s8, 2
	s_lshl_b32 s11, s9, 6
	v_lshl_or_b32 v0, s9, 13, v86
	s_or_b32 s9, s11, s10
	s_ashr_i32 s6, s0, 13
	v_lshl_or_b32 v156, s8, 7, v0
	v_mov_b32_e32 v68, s9
	s_load_dwordx2 s[8:9], s[90:91], 0x40
	s_ashr_i32 s7, s6, 31
	s_lshl_b64 s[6:7], s[6:7], 3
	s_add_u32 s6, s90, s6
	s_addc_u32 s7, s91, s7
	s_load_dwordx2 s[6:7], s[6:7], 0x10
	s_waitcnt lgkmcnt(0)
	global_load_dword v88, v68, s[8:9]
	s_cmpk_lt_u32 s0, 0x2000
	s_brev_b32 s8, 48
	s_cselect_b32 s8, s8, 0x14a00000
	s_add_u32 s8, s4, s8
	v_mov_b32_e32 v51, v157
	v_lshl_add_u64 v[60:61], v[156:157], 0, v[42:43]
	s_addc_u32 s9, s5, 0
	v_lshl_add_u64 v[0:1], v[156:157], 0, v[18:19]
	v_lshlrev_b64 v[90:91], 7, v[60:61]
	v_lshl_add_u64 v[60:61], s[8:9], 0, v[50:51]
	s_mov_b64 s[8:9], 0x800000
	v_lshlrev_b64 v[0:1], 7, v[0:1]
	v_lshl_add_u64 v[84:85], v[60:61], 0, s[8:9]
	v_lshl_add_u64 v[82:83], v[84:85], 0, v[0:1]
	s_mov_b32 s43, s21
	v_lshl_add_u64 v[54:55], v[156:157], 0, v[36:37]
	v_lshl_add_u64 v[62:63], v[156:157], 0, v[44:45]
	v_lshlrev_b64 v[54:55], 7, v[54:55]
	v_lshlrev_b64 v[92:93], 7, v[62:63]
	v_lshl_add_u64 v[62:63], v[84:85], 0, v[54:55]
	v_lshl_add_u64 v[54:55], v[84:85], 0, v[92:93]
	v_lshl_add_u64 v[2:3], v[156:157], 0, v[20:21]
	v_lshl_add_u64 v[4:5], v[156:157], 0, v[22:23]
	v_lshl_add_u64 v[6:7], v[156:157], 0, v[24:25]
	v_lshl_add_u64 v[8:9], v[156:157], 0, v[26:27]
	v_lshl_add_u64 v[10:11], v[156:157], 0, v[28:29]
	v_lshl_add_u64 v[12:13], v[156:157], 0, v[30:31]
	v_lshl_add_u64 v[14:15], v[156:157], 0, v[32:33]
	v_lshlrev_b64 v[2:3], 7, v[2:3]
	v_lshlrev_b64 v[4:5], 7, v[4:5]
	v_lshlrev_b64 v[6:7], 7, v[6:7]
	v_lshlrev_b64 v[8:9], 7, v[8:9]
	v_lshlrev_b64 v[10:11], 7, v[10:11]
	v_lshlrev_b64 v[12:13], 7, v[12:13]
	v_lshlrev_b64 v[14:15], 7, v[14:15]
	v_lshl_add_u64 v[80:81], v[84:85], 0, v[2:3]
	v_lshl_add_u64 v[78:79], v[84:85], 0, v[4:5]
	v_lshl_add_u64 v[76:77], v[84:85], 0, v[6:7]
	v_lshl_add_u64 v[74:75], v[84:85], 0, v[8:9]
	v_lshl_add_u64 v[72:73], v[84:85], 0, v[10:11]
	v_lshl_add_u64 v[70:71], v[84:85], 0, v[12:13]
	v_lshl_add_u64 v[68:69], v[84:85], 0, v[14:15]
	v_lshl_add_u64 v[52:53], v[156:157], 0, v[34:35]
	v_lshl_add_u64 v[56:57], v[156:157], 0, v[38:39]
	v_lshl_add_u64 v[64:65], v[156:157], 0, v[46:47]
	v_lshl_add_u64 v[66:67], v[156:157], 0, v[48:49]
	v_lshlrev_b64 v[52:53], 7, v[52:53]
	v_lshlrev_b64 v[56:57], 7, v[56:57]
	v_lshlrev_b64 v[94:95], 7, v[64:65]
	v_lshlrev_b64 v[64:65], 7, v[66:67]
	v_lshl_add_u64 v[66:67], v[84:85], 0, v[52:53]
	v_lshl_add_u64 v[60:61], v[84:85], 0, v[56:57]
	v_lshl_add_u64 v[56:57], v[84:85], 0, v[90:91]
	v_lshl_add_u64 v[52:53], v[84:85], 0, v[94:95]
	v_lshl_add_u64 v[58:59], v[156:157], 0, v[40:41]
	v_lshlrev_b64 v[58:59], 7, v[58:59]
	v_lshl_add_u64 v[58:59], v[84:85], 0, v[58:59]
	s_add_i32 s0, s0, s1
	s_cmpk_lt_i32 s0, 0x4000
	v_lshl_add_u64 v[64:65], v[84:85], 0, v[64:65]
	s_waitcnt vmcnt(0)
	v_ashrrev_i32_e32 v89, 31, v88
	v_lshlrev_b64 v[0:1], 17, v[88:89]
	v_lshl_add_u64 v[0:1], s[6:7], 0, v[0:1]
	v_lshl_add_u64 v[0:1], v[0:1], 0, s[42:43]
	v_lshl_add_u64 v[88:89], v[16:17], 2, v[0:1]
	s_mov_b64 s[6:7], 0x1000
	v_lshl_add_u64 v[92:93], v[88:89], 0, s[6:7]
	s_movk_i32 s6, 0x1000
	v_add_co_u32_e32 v96, vcc, s6, v88
	s_movk_i32 s6, 0x2000
	s_nop 0
	v_addc_co_u32_e32 v97, vcc, 0, v89, vcc
	v_add_co_u32_e32 v112, vcc, s6, v88
	s_mov_b64 s[6:7], 0x1800
	v_lshl_add_u64 v[100:101], v[88:89], 0, s[6:7]
	s_mov_b64 s[6:7], 0x2000
	v_lshl_add_u64 v[108:109], v[88:89], 0, s[6:7]
	s_mov_b64 s[6:7], 0x2800
	v_lshl_add_u64 v[116:117], v[88:89], 0, s[6:7]
	s_mov_b64 s[6:7], 0x3000
	v_addc_co_u32_e32 v113, vcc, 0, v89, vcc
	v_lshl_add_u64 v[124:125], v[88:89], 0, s[6:7]
	s_movk_i32 s6, 0x3000
	v_add_co_u32_e32 v128, vcc, s6, v88
	s_movk_i32 s6, 0x4000
	s_nop 0
	v_addc_co_u32_e32 v129, vcc, 0, v89, vcc
	v_add_co_u32_e32 v144, vcc, s6, v88
	s_mov_b64 s[6:7], 0x3800
	global_load_dwordx4 v[4:7], v[88:89], off offset:16 nt
	global_load_dwordx4 v[12:15], v[88:89], off nt
	global_load_dwordx4 v[0:3], v[88:89], off offset:2064 nt
	global_load_dwordx4 v[8:11], v[88:89], off offset:2048 nt
	v_lshl_add_u64 v[132:133], v[88:89], 0, s[6:7]
	s_mov_b64 s[6:7], 0x4000
	v_lshl_add_u64 v[140:141], v[88:89], 0, s[6:7]
	s_mov_b64 s[6:7], 0x4800
	v_lshl_add_u64 v[148:149], v[88:89], 0, s[6:7]
	s_mov_b64 s[6:7], 0x5000
	v_addc_co_u32_e32 v145, vcc, 0, v89, vcc
	v_lshl_add_u64 v[162:163], v[88:89], 0, s[6:7]
	s_movk_i32 s6, 0x5000
	v_add_co_u32_e32 v166, vcc, s6, v88
	s_movk_i32 s6, 0x6000
	s_nop 0
	v_addc_co_u32_e32 v167, vcc, 0, v89, vcc
	v_add_co_u32_e32 v182, vcc, s6, v88
	s_mov_b64 s[6:7], 0x5800
	v_lshl_add_u64 v[170:171], v[88:89], 0, s[6:7]
	s_mov_b64 s[6:7], 0x6000
	v_lshl_add_u64 v[178:179], v[88:89], 0, s[6:7]
	s_mov_b64 s[6:7], 0x6800
	v_lshl_add_u64 v[186:187], v[88:89], 0, s[6:7]
	s_mov_b64 s[6:7], 0x7000
	v_addc_co_u32_e32 v183, vcc, 0, v89, vcc
	v_lshl_add_u64 v[194:195], v[88:89], 0, s[6:7]
	s_movk_i32 s6, 0x7000
	v_add_co_u32_e32 v198, vcc, s6, v88
	s_mov_b64 s[6:7], 0x7800
	s_nop 0
	v_addc_co_u32_e32 v199, vcc, 0, v89, vcc
	v_lshl_add_u64 v[202:203], v[88:89], 0, s[6:7]
	global_load_dwordx4 v[88:91], v[112:113], off offset:-4096 nt
	s_nop 0
	global_load_dwordx4 v[92:95], v[92:93], off offset:16 nt
	s_nop 0
	global_load_dwordx4 v[96:99], v[96:97], off offset:2048 nt
	s_nop 0
; __device__ __forceinline__ unsigned pk2(float lo, float hi) { return cvt_pk_bf16(lo, hi); }
; __device__ __forceinline__ void cache_convert(const Params& P, const Ctx& C) {
;     ...
;         for (int j = 0; j < 16; ++j) { const float* sj = src + (size_t)(64 * j) * 8; a[j] = *(const f32x4*)(sj + 8u * lane); c[j] = *(const f32x4*)(sj + 8u * lane + 4); }
; #pragma unroll
;         for (int j = 0; j < 16; ++j) { const int q = lane + 64 * j, posn = qt * 32 + (q >> 5), g = (q & 31) >> 3, d0 = (q & 7) * 8;
;             u32x4 w; w.x = pk2(a[j][0], a[j][1]); w.y = pk2(a[j][2], a[j][3]); w.z = pk2(c[j][0], c[j][1]); w.w = pk2(c[j][2], c[j][3]);
;             *(u32x4*)(dst + ((size_t)(seq * 4 + g) * TC + pi * 128 + posn) * 64 + d0) = w; }
	global_load_dwordx4 v[100:103], v[100:101], off offset:16 nt
	s_nop 0
	global_load_dwordx4 v[104:107], v[112:113], off nt
	s_nop 0
	global_load_dwordx4 v[108:111], v[108:109], off offset:16 nt
	s_nop 0
	global_load_dwordx4 v[112:115], v[112:113], off offset:2048 nt
	s_nop 0
	global_load_dwordx4 v[116:119], v[116:117], off offset:16 nt
	s_nop 0
	global_load_dwordx4 v[120:123], v[144:145], off offset:-4096 nt
	s_nop 0
	global_load_dwordx4 v[124:127], v[124:125], off offset:16 nt
	s_nop 0
	global_load_dwordx4 v[128:131], v[128:129], off offset:2048 nt
	s_nop 0
	global_load_dwordx4 v[132:135], v[132:133], off offset:16 nt
	s_nop 0
	global_load_dwordx4 v[136:139], v[144:145], off nt
	s_nop 0
	global_load_dwordx4 v[140:143], v[140:141], off offset:16 nt
	s_nop 0
	global_load_dwordx4 v[144:147], v[144:145], off offset:2048 nt
	s_nop 0
	global_load_dwordx4 v[148:151], v[148:149], off offset:16 nt
	s_nop 0
	global_load_dwordx4 v[152:155], v[182:183], off offset:-4096 nt
	s_nop 0
	global_load_dwordx4 v[162:165], v[162:163], off offset:16 nt
	s_nop 0
	global_load_dwordx4 v[166:169], v[166:167], off offset:2048 nt
	s_nop 0
	global_load_dwordx4 v[170:173], v[170:171], off offset:16 nt
	s_nop 0
	global_load_dwordx4 v[174:177], v[182:183], off nt
	s_nop 0
	global_load_dwordx4 v[178:181], v[178:179], off offset:16 nt
	s_nop 0
	global_load_dwordx4 v[182:185], v[182:183], off offset:2048 nt
	s_nop 0
	global_load_dwordx4 v[186:189], v[186:187], off offset:16 nt
	s_nop 0
	global_load_dwordx4 v[190:193], v[198:199], off nt
	s_nop 0
	global_load_dwordx4 v[194:197], v[194:195], off offset:16 nt
	s_nop 0
	global_load_dwordx4 v[198:201], v[198:199], off offset:2048 nt
	s_nop 0
	global_load_dwordx4 v[206:209], v[202:203], off offset:16 nt
	s_waitcnt vmcnt(30)
	v_cvt_pk_bf16_f32 v12, v12, v13
	v_cvt_pk_bf16_f32 v13, v14, v15
	v_cvt_pk_bf16_f32 v14, v4, v5
	v_cvt_pk_bf16_f32 v15, v6, v7
	global_store_dwordx4 v[82:83], v[12:15], off
	s_waitcnt vmcnt(29)
	v_cvt_pk_bf16_f32 v4, v8, v9
	v_cvt_pk_bf16_f32 v5, v10, v11
	v_cvt_pk_bf16_f32 v6, v0, v1
	v_cvt_pk_bf16_f32 v7, v2, v3
	global_store_dwordx4 v[80:81], v[4:7], off
	s_waitcnt vmcnt(29)
	v_cvt_pk_bf16_f32 v0, v88, v89
	v_cvt_pk_bf16_f32 v1, v90, v91
	s_waitcnt vmcnt(28)
	v_cvt_pk_bf16_f32 v2, v92, v93
	v_cvt_pk_bf16_f32 v3, v94, v95
	global_store_dwordx4 v[78:79], v[0:3], off
	s_waitcnt vmcnt(28)
	s_nop 0
	v_cvt_pk_bf16_f32 v0, v96, v97
	v_cvt_pk_bf16_f32 v1, v98, v99
	s_waitcnt vmcnt(27)
	v_cvt_pk_bf16_f32 v2, v100, v101
	v_cvt_pk_bf16_f32 v3, v102, v103
	global_store_dwordx4 v[76:77], v[0:3], off
	s_waitcnt vmcnt(27)
	s_nop 0
	v_cvt_pk_bf16_f32 v0, v104, v105
	v_cvt_pk_bf16_f32 v1, v106, v107
	s_waitcnt vmcnt(26)
	v_cvt_pk_bf16_f32 v2, v108, v109
	v_cvt_pk_bf16_f32 v3, v110, v111
	global_store_dwordx4 v[74:75], v[0:3], off
	s_waitcnt vmcnt(26)
	s_nop 0
	v_cvt_pk_bf16_f32 v0, v112, v113
	v_cvt_pk_bf16_f32 v1, v114, v115
	s_waitcnt vmcnt(25)
	v_cvt_pk_bf16_f32 v2, v116, v117
	v_cvt_pk_bf16_f32 v3, v118, v119
	global_store_dwordx4 v[72:73], v[0:3], off
	s_waitcnt vmcnt(25)
	s_nop 0
	v_cvt_pk_bf16_f32 v0, v120, v121
	v_cvt_pk_bf16_f32 v1, v122, v123
	s_waitcnt vmcnt(24)
	v_cvt_pk_bf16_f32 v2, v124, v125
	v_cvt_pk_bf16_f32 v3, v126, v127
	global_store_dwordx4 v[70:71], v[0:3], off
	s_waitcnt vmcnt(24)
	s_nop 0
	v_cvt_pk_bf16_f32 v0, v128, v129
	v_cvt_pk_bf16_f32 v1, v130, v131
	s_waitcnt vmcnt(23)
	v_cvt_pk_bf16_f32 v2, v132, v133
	v_cvt_pk_bf16_f32 v3, v134, v135
	global_store_dwordx4 v[68:69], v[0:3], off
	s_waitcnt vmcnt(23)
	s_nop 0
	v_cvt_pk_bf16_f32 v0, v136, v137
	v_cvt_pk_bf16_f32 v1, v138, v139
	s_waitcnt vmcnt(22)
	v_cvt_pk_bf16_f32 v2, v140, v141
	v_cvt_pk_bf16_f32 v3, v142, v143
	global_store_dwordx4 v[66:67], v[0:3], off
	s_waitcnt vmcnt(22)
	s_nop 0
	v_cvt_pk_bf16_f32 v0, v144, v145
	v_cvt_pk_bf16_f32 v1, v146, v147
	s_waitcnt vmcnt(21)
	v_cvt_pk_bf16_f32 v2, v148, v149
	v_cvt_pk_bf16_f32 v3, v150, v151
	global_store_dwordx4 v[62:63], v[0:3], off
	s_waitcnt vmcnt(21)
	s_nop 0
	v_cvt_pk_bf16_f32 v0, v152, v153
	v_cvt_pk_bf16_f32 v1, v154, v155
	s_waitcnt vmcnt(20)
	v_cvt_pk_bf16_f32 v2, v162, v163
	v_cvt_pk_bf16_f32 v3, v164, v165
	global_store_dwordx4 v[60:61], v[0:3], off
	s_waitcnt vmcnt(20)
	s_nop 0
	v_cvt_pk_bf16_f32 v0, v166, v167
	v_cvt_pk_bf16_f32 v1, v168, v169
	s_waitcnt vmcnt(19)
	v_cvt_pk_bf16_f32 v2, v170, v171
	v_cvt_pk_bf16_f32 v3, v172, v173
	global_store_dwordx4 v[58:59], v[0:3], off
	s_waitcnt vmcnt(19)
	s_nop 0
	v_cvt_pk_bf16_f32 v0, v174, v175
	v_cvt_pk_bf16_f32 v1, v176, v177
	s_waitcnt vmcnt(18)
	v_cvt_pk_bf16_f32 v2, v178, v179
	v_cvt_pk_bf16_f32 v3, v180, v181
	global_store_dwordx4 v[56:57], v[0:3], off
	s_waitcnt vmcnt(18)
	s_nop 0
	v_cvt_pk_bf16_f32 v0, v182, v183
	v_cvt_pk_bf16_f32 v1, v184, v185
	s_waitcnt vmcnt(17)
	v_cvt_pk_bf16_f32 v2, v186, v187
	v_cvt_pk_bf16_f32 v3, v188, v189
	global_store_dwordx4 v[54:55], v[0:3], off
	s_waitcnt vmcnt(17)
	s_nop 0
	v_cvt_pk_bf16_f32 v0, v190, v191
	v_cvt_pk_bf16_f32 v1, v192, v193
	s_waitcnt vmcnt(16)
	v_cvt_pk_bf16_f32 v2, v194, v195
	v_cvt_pk_bf16_f32 v3, v196, v197
	global_store_dwordx4 v[52:53], v[0:3], off
	s_waitcnt vmcnt(16)
	s_nop 0
	v_cvt_pk_bf16_f32 v0, v198, v199
	v_cvt_pk_bf16_f32 v1, v200, v201
	s_waitcnt vmcnt(15)
	v_cvt_pk_bf16_f32 v2, v206, v207
	v_cvt_pk_bf16_f32 v3, v208, v209
	global_store_dwordx4 v[64:65], v[0:3], off
	s_cbranch_scc1 .LBB0_281
